# attnpro + grid barrier: non-leader L1 invalidate (buffer_inv sc1) issued right after arrival instead of after the release poll (L1 stays empty while the workgroup waits)
# speedup vs baseline: 1.0042x; 1.0042x over previous
; __device__ __forceinline__ unsigned xb_ld(unsigned* p)              { return __hip_atomic_load(p, __ATOMIC_RELAXED, __HIP_MEMORY_SCOPE_AGENT); }
; __device__ __forceinline__ unsigned xb_add(unsigned* p, unsigned v) { return __hip_atomic_fetch_add(p, v, __ATOMIC_RELAXED, __HIP_MEMORY_SCOPE_AGENT); }
; #define XB_SPIN(cond, bar) do { unsigned _sp = 0; while (cond) { __builtin_amdgcn_s_sleep(1); \
;     if ((++_sp & 255u) == 0u) { if (xb_ld(&(bar)[XB_TMO])) break; if (_sp > XB_SPIN_CAP) { atomicAdd(&(bar)[XB_TMO], 1u); break; } } } } while (0)
; __device__ __forceinline__ void xcd_barrier(const XcdBarrier& b) {
;     ...
;         const unsigned old = xb_add(&bar[XB_XSUB(b.x)], 1u);
;         const unsigned gen = old / nloc;
;         if (old + 1u == (gen + 1u) * nloc) {
;             __builtin_amdgcn_fence(__ATOMIC_RELEASE, "agent");
;             asm volatile("s_waitcnt vmcnt(0)" ::: "memory");
;             const unsigned og = xb_add(&bar[XB_TOP], 1u);
;             const unsigned tg = og / nx;
;             if (og + 1u == (tg + 1u) * nx) xb_add(&bar[XB_TOPGEN], 1u);
;             else XB_SPIN(xb_ld(&bar[XB_TOPGEN]) == tg, bar);
;             __builtin_amdgcn_fence(__ATOMIC_ACQUIRE, "agent");
;             xb_add(&bar[XB_XGEN(b.x)], 1u);
;             asm volatile("s_waitcnt vmcnt(0)" ::: "memory");
;         } else {
;             XB_SPIN(xb_ld(&bar[XB_XGEN(b.x)]) == gen, bar);
;             __builtin_amdgcn_fence(__ATOMIC_ACQUIRE, "agent");
.LBB0_603:
	s_or_b64 exec, exec, s[18:19]
	v_cvt_f32_u32_e32 v4, v2
	s_waitcnt vmcnt(0)
	v_readfirstlane_b32 s2, v3
	v_sub_u32_e32 v3, 0, v2
	v_rcp_iflag_f32_e32 v4, v4
	v_add_u32_e32 v5, s2, v1
	v_mul_f32_e32 v4, 0x4f7ffffe, v4
	v_cvt_u32_f32_e32 v4, v4
	v_mul_lo_u32 v1, v3, v4
	v_mul_hi_u32 v1, v4, v1
	v_add_u32_e32 v1, v4, v1
	v_mul_hi_u32 v1, v5, v1
	v_mul_lo_u32 v3, v1, v2
	v_sub_u32_e32 v3, v5, v3
	v_add_u32_e32 v4, 1, v1
	v_cmp_ge_u32_e32 vcc, v3, v2
	s_nop 1
	v_cndmask_b32_e32 v1, v1, v4, vcc
	v_sub_u32_e32 v4, v3, v2
	v_cndmask_b32_e32 v3, v3, v4, vcc
	v_add_u32_e32 v4, 1, v1
	v_cmp_ge_u32_e32 vcc, v3, v2
	v_add_u32_e32 v3, 1, v5
	s_nop 0
	v_cndmask_b32_e32 v1, v1, v4, vcc
	v_mul_lo_u32 v4, v2, v1
	v_add_u32_e32 v2, v4, v2
	v_cmp_ne_u32_e32 vcc, v3, v2
	s_and_saveexec_b64 s[18:19], vcc
	s_xor_b64 s[18:19], exec, s[18:19]
	s_cbranch_execz .LBB0_617
	buffer_inv sc1
	v_readlane_b32 s4, v253, 52
	v_readlane_b32 s5, v253, 53
	s_waitcnt lgkmcnt(0)
	s_nop 3
	global_load_dword v0, v144, s[4:5] sc1
	s_waitcnt vmcnt(0)
	v_cmp_eq_u32_e32 vcc, v0, v1
	s_and_saveexec_b64 s[20:21], vcc
	s_cbranch_execz .LBB0_616
	s_mov_b32 s2, 1
	s_mov_b64 s[28:29], 0
	s_branch .LBB0_607

; __device__ __forceinline__ unsigned xb_ld(unsigned* p)              { return __hip_atomic_load(p, __ATOMIC_RELAXED, __HIP_MEMORY_SCOPE_AGENT); }
; #define XB_SPIN(cond, bar) do { unsigned _sp = 0; while (cond) { __builtin_amdgcn_s_sleep(1); \
;     if ((++_sp & 255u) == 0u) { if (xb_ld(&(bar)[XB_TMO])) break; if (_sp > XB_SPIN_CAP) { atomicAdd(&(bar)[XB_TMO], 1u); break; } } } } while (0)
; __device__ __forceinline__ void xcd_barrier(const XcdBarrier& b) {
;     ...
;             XB_SPIN(xb_ld(&bar[XB_XGEN(b.x)]) == gen, bar);
;             __builtin_amdgcn_fence(__ATOMIC_ACQUIRE, "agent");
;             asm volatile("s_waitcnt vmcnt(0)" ::: "memory");
.LBB0_616:
	s_or_b64 exec, exec, s[20:21]
	s_waitcnt vmcnt(0)
	s_waitcnt vmcnt(0)
